# final RMSNorm row loop rewritten by hand: gains kept in registers, whole row loaded at once with the next row prefetched into a second buffer (same math and operation order)
# speedup vs baseline: 1.0269x; 1.0006x over previous
; #define LAUNDER() asm volatile("v_mbcnt_lo_u32_b32 %0, -1, 0\n\tv_mbcnt_hi_u32_b32 %0, -1, %0" : "=v"(lane))
; __global__ void __launch_bounds__(NWAVES * 64, 2) mega_fwd(Args args) {
;     ...
;     if (IN(1 + 5 * DEPTH)) {
;         LAUNDER();
;         const float* sq = SSQ + (size_t)(2 * DEPTH) * M;
;         for (int m = gw; m < M; m += NGW) { f32x4* xr = (f32x4*)(out + (size_t)m * DM) + lane; const f32x4* gr = (const f32x4*)fin_g + lane; const float rs = 1.f / sqrtf(sq[m] * (1.f / DM) + 1e-6f);
; #pragma unroll
;             for (int j = 0; j < 8; ++j) xr[64 * j] = xr[64 * j] * rs * gr[64 * j]; }
;     }
.LBB0_590:
	s_cmp_lt_i32 s54, 12
	s_cselect_b64 s[0:1], -1, 0
	s_cmp_gt_i32 s55, 11
	s_cselect_b64 s[2:3], -1, 0
	s_and_b64 s[0:1], s[0:1], s[2:3]
	s_and_b64 vcc, exec, s[0:1]
	v_readlane_b32 s10, v254, 15
	v_readlane_b32 s11, v254, 16
	s_cbranch_vccz .LBB0_594
	s_cmp_gt_i32 s10, 0x9fff
	v_mbcnt_lo_u32_b32 v0, -1, 0
	v_mbcnt_hi_u32_b32 v0, -1, v0
	s_cbranch_scc1 .LBB0_594
	s_ashr_i32 s11, s10, 31
	s_lshl_b64 s[2:3], s[10:11], 2
	s_add_u32 s2, s30, s2
	s_addc_u32 s3, s31, s3
	v_readlane_b32 s12, v254, 13
	s_waitcnt lgkmcnt(0)
	v_ashrrev_i32_e32 v1, 31, v0
	s_add_u32 s2, s2, 0xa0000
	v_readlane_b32 s13, v254, 14
	v_lshlrev_b64 v[10:11], 4, v[0:1]
	s_addc_u32 s3, s3, 0
	s_ashr_i32 s13, s12, 31
	v_lshl_add_u64 v[0:1], s[50:51], 0, v[10:11]
	s_mov_b64 s[0:1], 0x1000
	s_lshl_b64 s[4:5], s[12:13], 2
	s_lshl_b64 s[6:7], s[10:11], 13
	v_lshl_add_u64 v[2:3], v[0:1], 0, s[0:1]
	s_mov_b64 s[0:1], 0x1400
	s_add_u32 s6, s28, s6
	v_lshl_add_u64 v[4:5], v[0:1], 0, s[0:1]
	s_mov_b64 s[0:1], 0x1800
	s_addc_u32 s7, s29, s7
	v_lshl_add_u64 v[6:7], v[0:1], 0, s[0:1]
	s_mov_b64 s[0:1], 0x1c00
	v_lshl_add_u64 v[10:11], s[6:7], 0, v[10:11]
	v_lshl_add_u64 v[8:9], v[0:1], 0, s[0:1]
	v_lshl_add_u64 v[10:11], v[10:11], 0, s[0:1]
	s_lshl_b64 s[6:7], s[12:13], 13
	v_mov_b32_e32 v12, 0
	v_mov_b32_e32 v13, 0x358637bd
	s_mov_b32 s8, 0xf800000
	v_mov_b32_e32 v14, 0x260
	s_movk_i32 s9, 0xf000
	global_load_dwordx4 v[64:67], v[0:1], off
	global_load_dwordx4 v[68:71], v[0:1], off offset:1024
	global_load_dwordx4 v[72:75], v[0:1], off offset:2048
	global_load_dwordx4 v[76:79], v[0:1], off offset:3072
	global_load_dwordx4 v[80:83], v[2:3], off
	global_load_dwordx4 v[84:87], v[4:5], off
	global_load_dwordx4 v[88:91], v[6:7], off
	global_load_dwordx4 v[92:95], v[8:9], off
	global_load_dword v40, v12, s[2:3]
	v_add_co_u32_e32 v28, vcc, s9, v10
	s_nop 1
	v_addc_co_u32_e32 v29, vcc, -1, v11, vcc
	global_load_dwordx4 v[96:99], v[28:29], off offset:-3072
	global_load_dwordx4 v[100:103], v[28:29], off offset:-2048
	global_load_dwordx4 v[104:107], v[28:29], off offset:-1024
	global_load_dwordx4 v[108:111], v[10:11], off offset:-4096
	global_load_dwordx4 v[112:115], v[10:11], off offset:-3072
	global_load_dwordx4 v[116:119], v[10:11], off offset:-2048
	global_load_dwordx4 v[120:123], v[10:11], off offset:-1024
	global_load_dwordx4 v[124:127], v[10:11], off
.Lmy_fn_loop:
	s_add_i32 s10, s10, s12
	s_cmp_lt_i32 s10, 0xa000
	s_cbranch_scc0 .Lmy_fn_lastA
	v_mov_b32_e32 v36, v10
	v_mov_b32_e32 v37, v11
	v_lshl_add_u64 v[10:11], v[10:11], 0, s[6:7]
	s_add_u32 s2, s2, s4
	s_addc_u32 s3, s3, s5
	global_load_dword v35, v12, s[2:3]
	v_add_co_u32_e32 v28, vcc, s9, v10
	s_nop 1
	v_addc_co_u32_e32 v29, vcc, -1, v11, vcc
	global_load_dwordx4 v[128:131], v[28:29], off offset:-3072
	global_load_dwordx4 v[132:135], v[28:29], off offset:-2048
	global_load_dwordx4 v[136:139], v[28:29], off offset:-1024
	global_load_dwordx4 v[140:143], v[10:11], off offset:-4096
	global_load_dwordx4 v[144:147], v[10:11], off offset:-3072
	global_load_dwordx4 v[148:151], v[10:11], off offset:-2048
	global_load_dwordx4 v[152:155], v[10:11], off offset:-1024
	global_load_dwordx4 v[156:159], v[10:11], off
	s_waitcnt vmcnt(9)
	v_mov_b32_e32 v15, v40
	v_fmamk_f32 v15, v15, 0x3a000000, v13
	v_mul_f32_e32 v30, 0x4f800000, v15
	v_cmp_gt_f32_e32 vcc, s8, v15
	s_nop 1
	v_cndmask_b32_e32 v15, v15, v30, vcc
	v_sqrt_f32_e32 v30, v15
	s_nop 0
	v_add_u32_e32 v31, -1, v30
	v_add_u32_e32 v32, 1, v30
	v_fma_f32 v33, -v31, v30, v15
	v_fma_f32 v34, -v32, v30, v15
	v_cmp_ge_f32_e64 s[0:1], 0, v33
	s_nop 1
	v_cndmask_b32_e64 v30, v30, v31, s[0:1]
	v_cmp_lt_f32_e64 s[0:1], 0, v34
	s_nop 1
	v_cndmask_b32_e64 v30, v30, v32, s[0:1]
	v_mul_f32_e32 v31, 0x37800000, v30
	v_cndmask_b32_e32 v30, v30, v31, vcc
	v_cmp_class_f32_e32 vcc, v15, v14
	s_nop 1
	v_cndmask_b32_e32 v15, v30, v15, vcc
	v_div_scale_f32 v30, s[0:1], v15, v15, 1.0
	v_rcp_f32_e32 v32, v30
	v_div_scale_f32 v31, vcc, 1.0, v15, 1.0
	v_fma_f32 v33, -v30, v32, 1.0
	v_fmac_f32_e32 v32, v33, v32
	v_mul_f32_e32 v33, v31, v32
	v_fma_f32 v34, -v30, v33, v31
	v_fmac_f32_e32 v33, v34, v32
	v_fma_f32 v30, -v30, v33, v31
	v_div_fmas_f32 v30, v30, v32, v33
	v_div_fixup_f32 v30, v30, v15, 1.0
	v_pk_mul_f32 v[96:97], v[30:31], v[96:97] op_sel_hi:[0,1]
	v_pk_mul_f32 v[98:99], v[30:31], v[98:99] op_sel_hi:[0,1]
	v_pk_mul_f32 v[96:97], v[96:97], v[64:65]
	v_pk_mul_f32 v[98:99], v[98:99], v[66:67]
	v_pk_mul_f32 v[100:101], v[30:31], v[100:101] op_sel_hi:[0,1]
	v_pk_mul_f32 v[102:103], v[30:31], v[102:103] op_sel_hi:[0,1]
	v_pk_mul_f32 v[100:101], v[100:101], v[68:69]
	v_pk_mul_f32 v[102:103], v[102:103], v[70:71]
	v_pk_mul_f32 v[104:105], v[30:31], v[104:105] op_sel_hi:[0,1]
	v_pk_mul_f32 v[106:107], v[30:31], v[106:107] op_sel_hi:[0,1]
	v_pk_mul_f32 v[104:105], v[104:105], v[72:73]
	v_pk_mul_f32 v[106:107], v[106:107], v[74:75]
	v_pk_mul_f32 v[108:109], v[30:31], v[108:109] op_sel_hi:[0,1]
	v_pk_mul_f32 v[110:111], v[30:31], v[110:111] op_sel_hi:[0,1]
	v_pk_mul_f32 v[108:109], v[108:109], v[76:77]
	v_pk_mul_f32 v[110:111], v[110:111], v[78:79]
	v_pk_mul_f32 v[112:113], v[30:31], v[112:113] op_sel_hi:[0,1]
	v_pk_mul_f32 v[114:115], v[30:31], v[114:115] op_sel_hi:[0,1]
	v_pk_mul_f32 v[112:113], v[112:113], v[80:81]
	v_pk_mul_f32 v[114:115], v[114:115], v[82:83]
	v_pk_mul_f32 v[116:117], v[30:31], v[116:117] op_sel_hi:[0,1]
	v_pk_mul_f32 v[118:119], v[30:31], v[118:119] op_sel_hi:[0,1]
	v_pk_mul_f32 v[116:117], v[116:117], v[84:85]
	v_pk_mul_f32 v[118:119], v[118:119], v[86:87]
	v_pk_mul_f32 v[120:121], v[30:31], v[120:121] op_sel_hi:[0,1]
	v_pk_mul_f32 v[122:123], v[30:31], v[122:123] op_sel_hi:[0,1]
	v_pk_mul_f32 v[120:121], v[120:121], v[88:89]
	v_pk_mul_f32 v[122:123], v[122:123], v[90:91]
	v_pk_mul_f32 v[124:125], v[30:31], v[124:125] op_sel_hi:[0,1]
	v_pk_mul_f32 v[126:127], v[30:31], v[126:127] op_sel_hi:[0,1]
	v_pk_mul_f32 v[124:125], v[124:125], v[92:93]
	v_pk_mul_f32 v[126:127], v[126:127], v[94:95]
	v_add_co_u32_e32 v38, vcc, s9, v36
	s_nop 1
	v_addc_co_u32_e32 v39, vcc, -1, v37, vcc
	global_store_dwordx4 v[38:39], v[96:99], off offset:-3072
	global_store_dwordx4 v[38:39], v[100:103], off offset:-2048
	global_store_dwordx4 v[38:39], v[104:107], off offset:-1024
	global_store_dwordx4 v[36:37], v[108:111], off offset:-4096
	global_store_dwordx4 v[36:37], v[112:115], off offset:-3072
	global_store_dwordx4 v[36:37], v[116:119], off offset:-2048
	global_store_dwordx4 v[36:37], v[120:123], off offset:-1024
	global_store_dwordx4 v[36:37], v[124:127], off
	s_add_i32 s10, s10, s12
	s_cmp_lt_i32 s10, 0xa000
	s_cbranch_scc0 .Lmy_fn_lastB
; __global__ void __launch_bounds__(NWAVES * 64, 2) mega_fwd(Args args) {
;     ...
;         for (int m = gw; m < M; m += NGW) { f32x4* xr = (f32x4*)(out + (size_t)m * DM) + lane; const f32x4* gr = (const f32x4*)fin_g + lane; const float rs = 1.f / sqrtf(sq[m] * (1.f / DM) + 1e-6f);
; #pragma unroll
;             for (int j = 0; j < 8; ++j) xr[64 * j] = xr[64 * j] * rs * gr[64 * j]; }
	v_mov_b32_e32 v36, v10
	v_mov_b32_e32 v37, v11
	v_lshl_add_u64 v[10:11], v[10:11], 0, s[6:7]
	s_add_u32 s2, s2, s4
	s_addc_u32 s3, s3, s5
	global_load_dword v40, v12, s[2:3]
	v_add_co_u32_e32 v28, vcc, s9, v10
	s_nop 1
	v_addc_co_u32_e32 v29, vcc, -1, v11, vcc
	global_load_dwordx4 v[96:99], v[28:29], off offset:-3072
	global_load_dwordx4 v[100:103], v[28:29], off offset:-2048
	global_load_dwordx4 v[104:107], v[28:29], off offset:-1024
	global_load_dwordx4 v[108:111], v[10:11], off offset:-4096
	global_load_dwordx4 v[112:115], v[10:11], off offset:-3072
	global_load_dwordx4 v[116:119], v[10:11], off offset:-2048
	global_load_dwordx4 v[120:123], v[10:11], off offset:-1024
	global_load_dwordx4 v[124:127], v[10:11], off
	s_waitcnt vmcnt(9)
	v_mov_b32_e32 v15, v35
	v_fmamk_f32 v15, v15, 0x3a000000, v13
	v_mul_f32_e32 v30, 0x4f800000, v15
	v_cmp_gt_f32_e32 vcc, s8, v15
	s_nop 1
	v_cndmask_b32_e32 v15, v15, v30, vcc
	v_sqrt_f32_e32 v30, v15
	s_nop 0
	v_add_u32_e32 v31, -1, v30
	v_add_u32_e32 v32, 1, v30
	v_fma_f32 v33, -v31, v30, v15
	v_fma_f32 v34, -v32, v30, v15
	v_cmp_ge_f32_e64 s[0:1], 0, v33
	s_nop 1
	v_cndmask_b32_e64 v30, v30, v31, s[0:1]
	v_cmp_lt_f32_e64 s[0:1], 0, v34
	s_nop 1
	v_cndmask_b32_e64 v30, v30, v32, s[0:1]
	v_mul_f32_e32 v31, 0x37800000, v30
	v_cndmask_b32_e32 v30, v30, v31, vcc
	v_cmp_class_f32_e32 vcc, v15, v14
	s_nop 1
	v_cndmask_b32_e32 v15, v30, v15, vcc
	v_div_scale_f32 v30, s[0:1], v15, v15, 1.0
	v_rcp_f32_e32 v32, v30
	v_div_scale_f32 v31, vcc, 1.0, v15, 1.0
	v_fma_f32 v33, -v30, v32, 1.0
	v_fmac_f32_e32 v32, v33, v32
	v_mul_f32_e32 v33, v31, v32
	v_fma_f32 v34, -v30, v33, v31
	v_fmac_f32_e32 v33, v34, v32
	v_fma_f32 v30, -v30, v33, v31
	v_div_fmas_f32 v30, v30, v32, v33
	v_div_fixup_f32 v30, v30, v15, 1.0
	v_pk_mul_f32 v[128:129], v[30:31], v[128:129] op_sel_hi:[0,1]
	v_pk_mul_f32 v[130:131], v[30:31], v[130:131] op_sel_hi:[0,1]
	v_pk_mul_f32 v[128:129], v[128:129], v[64:65]
	v_pk_mul_f32 v[130:131], v[130:131], v[66:67]
	v_pk_mul_f32 v[132:133], v[30:31], v[132:133] op_sel_hi:[0,1]
	v_pk_mul_f32 v[134:135], v[30:31], v[134:135] op_sel_hi:[0,1]
	v_pk_mul_f32 v[132:133], v[132:133], v[68:69]
	v_pk_mul_f32 v[134:135], v[134:135], v[70:71]
	v_pk_mul_f32 v[136:137], v[30:31], v[136:137] op_sel_hi:[0,1]
	v_pk_mul_f32 v[138:139], v[30:31], v[138:139] op_sel_hi:[0,1]
	v_pk_mul_f32 v[136:137], v[136:137], v[72:73]
	v_pk_mul_f32 v[138:139], v[138:139], v[74:75]
	v_pk_mul_f32 v[140:141], v[30:31], v[140:141] op_sel_hi:[0,1]
	v_pk_mul_f32 v[142:143], v[30:31], v[142:143] op_sel_hi:[0,1]
	v_pk_mul_f32 v[140:141], v[140:141], v[76:77]
	v_pk_mul_f32 v[142:143], v[142:143], v[78:79]
	v_pk_mul_f32 v[144:145], v[30:31], v[144:145] op_sel_hi:[0,1]
	v_pk_mul_f32 v[146:147], v[30:31], v[146:147] op_sel_hi:[0,1]
	v_pk_mul_f32 v[144:145], v[144:145], v[80:81]
	v_pk_mul_f32 v[146:147], v[146:147], v[82:83]
	v_pk_mul_f32 v[148:149], v[30:31], v[148:149] op_sel_hi:[0,1]
	v_pk_mul_f32 v[150:151], v[30:31], v[150:151] op_sel_hi:[0,1]
	v_pk_mul_f32 v[148:149], v[148:149], v[84:85]
	v_pk_mul_f32 v[150:151], v[150:151], v[86:87]
	v_pk_mul_f32 v[152:153], v[30:31], v[152:153] op_sel_hi:[0,1]
	v_pk_mul_f32 v[154:155], v[30:31], v[154:155] op_sel_hi:[0,1]
	v_pk_mul_f32 v[152:153], v[152:153], v[88:89]
	v_pk_mul_f32 v[154:155], v[154:155], v[90:91]
	v_pk_mul_f32 v[156:157], v[30:31], v[156:157] op_sel_hi:[0,1]
	v_pk_mul_f32 v[158:159], v[30:31], v[158:159] op_sel_hi:[0,1]
	v_pk_mul_f32 v[156:157], v[156:157], v[92:93]
	v_pk_mul_f32 v[158:159], v[158:159], v[94:95]
	v_add_co_u32_e32 v38, vcc, s9, v36
	s_nop 1
	v_addc_co_u32_e32 v39, vcc, -1, v37, vcc
	global_store_dwordx4 v[38:39], v[128:131], off offset:-3072
	global_store_dwordx4 v[38:39], v[132:135], off offset:-2048
	global_store_dwordx4 v[38:39], v[136:139], off offset:-1024
	global_store_dwordx4 v[36:37], v[140:143], off offset:-4096
	global_store_dwordx4 v[36:37], v[144:147], off offset:-3072
	global_store_dwordx4 v[36:37], v[148:151], off offset:-2048
	global_store_dwordx4 v[36:37], v[152:155], off offset:-1024
	global_store_dwordx4 v[36:37], v[156:159], off
	s_branch .Lmy_fn_loop
; __global__ void __launch_bounds__(NWAVES * 64, 2) mega_fwd(Args args) {
;     ...
;         for (int m = gw; m < M; m += NGW) { f32x4* xr = (f32x4*)(out + (size_t)m * DM) + lane; const f32x4* gr = (const f32x4*)fin_g + lane; const float rs = 1.f / sqrtf(sq[m] * (1.f / DM) + 1e-6f);
; #pragma unroll
;             for (int j = 0; j < 8; ++j) xr[64 * j] = xr[64 * j] * rs * gr[64 * j]; }
.Lmy_fn_lastA:
	s_waitcnt vmcnt(0)
	v_mov_b32_e32 v15, v40
	v_fmamk_f32 v15, v15, 0x3a000000, v13
	v_mul_f32_e32 v30, 0x4f800000, v15
	v_cmp_gt_f32_e32 vcc, s8, v15
	s_nop 1
	v_cndmask_b32_e32 v15, v15, v30, vcc
	v_sqrt_f32_e32 v30, v15
	s_nop 0
	v_add_u32_e32 v31, -1, v30
	v_add_u32_e32 v32, 1, v30
	v_fma_f32 v33, -v31, v30, v15
	v_fma_f32 v34, -v32, v30, v15
	v_cmp_ge_f32_e64 s[0:1], 0, v33
	s_nop 1
	v_cndmask_b32_e64 v30, v30, v31, s[0:1]
	v_cmp_lt_f32_e64 s[0:1], 0, v34
	s_nop 1
	v_cndmask_b32_e64 v30, v30, v32, s[0:1]
	v_mul_f32_e32 v31, 0x37800000, v30
	v_cndmask_b32_e32 v30, v30, v31, vcc
	v_cmp_class_f32_e32 vcc, v15, v14
	s_nop 1
	v_cndmask_b32_e32 v15, v30, v15, vcc
	v_div_scale_f32 v30, s[0:1], v15, v15, 1.0
	v_rcp_f32_e32 v32, v30
	v_div_scale_f32 v31, vcc, 1.0, v15, 1.0
	v_fma_f32 v33, -v30, v32, 1.0
	v_fmac_f32_e32 v32, v33, v32
	v_mul_f32_e32 v33, v31, v32
	v_fma_f32 v34, -v30, v33, v31
	v_fmac_f32_e32 v33, v34, v32
	v_fma_f32 v30, -v30, v33, v31
	v_div_fmas_f32 v30, v30, v32, v33
	v_div_fixup_f32 v30, v30, v15, 1.0
	v_pk_mul_f32 v[96:97], v[30:31], v[96:97] op_sel_hi:[0,1]
	v_pk_mul_f32 v[98:99], v[30:31], v[98:99] op_sel_hi:[0,1]
	v_pk_mul_f32 v[96:97], v[96:97], v[64:65]
	v_pk_mul_f32 v[98:99], v[98:99], v[66:67]
	v_pk_mul_f32 v[100:101], v[30:31], v[100:101] op_sel_hi:[0,1]
	v_pk_mul_f32 v[102:103], v[30:31], v[102:103] op_sel_hi:[0,1]
	v_pk_mul_f32 v[100:101], v[100:101], v[68:69]
	v_pk_mul_f32 v[102:103], v[102:103], v[70:71]
	v_pk_mul_f32 v[104:105], v[30:31], v[104:105] op_sel_hi:[0,1]
	v_pk_mul_f32 v[106:107], v[30:31], v[106:107] op_sel_hi:[0,1]
	v_pk_mul_f32 v[104:105], v[104:105], v[72:73]
	v_pk_mul_f32 v[106:107], v[106:107], v[74:75]
	v_pk_mul_f32 v[108:109], v[30:31], v[108:109] op_sel_hi:[0,1]
	v_pk_mul_f32 v[110:111], v[30:31], v[110:111] op_sel_hi:[0,1]
	v_pk_mul_f32 v[108:109], v[108:109], v[76:77]
	v_pk_mul_f32 v[110:111], v[110:111], v[78:79]
	v_pk_mul_f32 v[112:113], v[30:31], v[112:113] op_sel_hi:[0,1]
	v_pk_mul_f32 v[114:115], v[30:31], v[114:115] op_sel_hi:[0,1]
	v_pk_mul_f32 v[112:113], v[112:113], v[80:81]
	v_pk_mul_f32 v[114:115], v[114:115], v[82:83]
	v_pk_mul_f32 v[116:117], v[30:31], v[116:117] op_sel_hi:[0,1]
	v_pk_mul_f32 v[118:119], v[30:31], v[118:119] op_sel_hi:[0,1]
	v_pk_mul_f32 v[116:117], v[116:117], v[84:85]
	v_pk_mul_f32 v[118:119], v[118:119], v[86:87]
	v_pk_mul_f32 v[120:121], v[30:31], v[120:121] op_sel_hi:[0,1]
	v_pk_mul_f32 v[122:123], v[30:31], v[122:123] op_sel_hi:[0,1]
	v_pk_mul_f32 v[120:121], v[120:121], v[88:89]
	v_pk_mul_f32 v[122:123], v[122:123], v[90:91]
	v_pk_mul_f32 v[124:125], v[30:31], v[124:125] op_sel_hi:[0,1]
	v_pk_mul_f32 v[126:127], v[30:31], v[126:127] op_sel_hi:[0,1]
	v_pk_mul_f32 v[124:125], v[124:125], v[92:93]
	v_pk_mul_f32 v[126:127], v[126:127], v[94:95]
	v_add_co_u32_e32 v38, vcc, s9, v10
	s_nop 1
	v_addc_co_u32_e32 v39, vcc, -1, v11, vcc
	global_store_dwordx4 v[38:39], v[96:99], off offset:-3072
	global_store_dwordx4 v[38:39], v[100:103], off offset:-2048
	global_store_dwordx4 v[38:39], v[104:107], off offset:-1024
	global_store_dwordx4 v[10:11], v[108:111], off offset:-4096
	global_store_dwordx4 v[10:11], v[112:115], off offset:-3072
	global_store_dwordx4 v[10:11], v[116:119], off offset:-2048
	global_store_dwordx4 v[10:11], v[120:123], off offset:-1024
	global_store_dwordx4 v[10:11], v[124:127], off
	s_endpgm
.Lmy_fn_lastB:
	s_waitcnt vmcnt(0)
	v_mov_b32_e32 v15, v35
	v_fmamk_f32 v15, v15, 0x3a000000, v13
	v_mul_f32_e32 v30, 0x4f800000, v15
	v_cmp_gt_f32_e32 vcc, s8, v15
	s_nop 1
	v_cndmask_b32_e32 v15, v15, v30, vcc
	v_sqrt_f32_e32 v30, v15
	s_nop 0
	v_add_u32_e32 v31, -1, v30
	v_add_u32_e32 v32, 1, v30
	v_fma_f32 v33, -v31, v30, v15
	v_fma_f32 v34, -v32, v30, v15
	v_cmp_ge_f32_e64 s[0:1], 0, v33
	s_nop 1
	v_cndmask_b32_e64 v30, v30, v31, s[0:1]
	v_cmp_lt_f32_e64 s[0:1], 0, v34
	s_nop 1
	v_cndmask_b32_e64 v30, v30, v32, s[0:1]
	v_mul_f32_e32 v31, 0x37800000, v30
	v_cndmask_b32_e32 v30, v30, v31, vcc
	v_cmp_class_f32_e32 vcc, v15, v14
	s_nop 1
	v_cndmask_b32_e32 v15, v30, v15, vcc
	v_div_scale_f32 v30, s[0:1], v15, v15, 1.0
	v_rcp_f32_e32 v32, v30
	v_div_scale_f32 v31, vcc, 1.0, v15, 1.0
	v_fma_f32 v33, -v30, v32, 1.0
	v_fmac_f32_e32 v32, v33, v32
	v_mul_f32_e32 v33, v31, v32
	v_fma_f32 v34, -v30, v33, v31
	v_fmac_f32_e32 v33, v34, v32
	v_fma_f32 v30, -v30, v33, v31
	v_div_fmas_f32 v30, v30, v32, v33
	v_div_fixup_f32 v30, v30, v15, 1.0
	v_pk_mul_f32 v[128:129], v[30:31], v[128:129] op_sel_hi:[0,1]
	v_pk_mul_f32 v[130:131], v[30:31], v[130:131] op_sel_hi:[0,1]
	v_pk_mul_f32 v[128:129], v[128:129], v[64:65]
	v_pk_mul_f32 v[130:131], v[130:131], v[66:67]
	v_pk_mul_f32 v[132:133], v[30:31], v[132:133] op_sel_hi:[0,1]
	v_pk_mul_f32 v[134:135], v[30:31], v[134:135] op_sel_hi:[0,1]
	v_pk_mul_f32 v[132:133], v[132:133], v[68:69]
	v_pk_mul_f32 v[134:135], v[134:135], v[70:71]
	v_pk_mul_f32 v[136:137], v[30:31], v[136:137] op_sel_hi:[0,1]
	v_pk_mul_f32 v[138:139], v[30:31], v[138:139] op_sel_hi:[0,1]
	v_pk_mul_f32 v[136:137], v[136:137], v[72:73]
	v_pk_mul_f32 v[138:139], v[138:139], v[74:75]
	v_pk_mul_f32 v[140:141], v[30:31], v[140:141] op_sel_hi:[0,1]
	v_pk_mul_f32 v[142:143], v[30:31], v[142:143] op_sel_hi:[0,1]
	v_pk_mul_f32 v[140:141], v[140:141], v[76:77]
	v_pk_mul_f32 v[142:143], v[142:143], v[78:79]
	v_pk_mul_f32 v[144:145], v[30:31], v[144:145] op_sel_hi:[0,1]
	v_pk_mul_f32 v[146:147], v[30:31], v[146:147] op_sel_hi:[0,1]
	v_pk_mul_f32 v[144:145], v[144:145], v[80:81]
	v_pk_mul_f32 v[146:147], v[146:147], v[82:83]
	v_pk_mul_f32 v[148:149], v[30:31], v[148:149] op_sel_hi:[0,1]
	v_pk_mul_f32 v[150:151], v[30:31], v[150:151] op_sel_hi:[0,1]
	v_pk_mul_f32 v[148:149], v[148:149], v[84:85]
	v_pk_mul_f32 v[150:151], v[150:151], v[86:87]
	v_pk_mul_f32 v[152:153], v[30:31], v[152:153] op_sel_hi:[0,1]
	v_pk_mul_f32 v[154:155], v[30:31], v[154:155] op_sel_hi:[0,1]
	v_pk_mul_f32 v[152:153], v[152:153], v[88:89]
	v_pk_mul_f32 v[154:155], v[154:155], v[90:91]
	v_pk_mul_f32 v[156:157], v[30:31], v[156:157] op_sel_hi:[0,1]
	v_pk_mul_f32 v[158:159], v[30:31], v[158:159] op_sel_hi:[0,1]
	v_pk_mul_f32 v[156:157], v[156:157], v[92:93]
	v_pk_mul_f32 v[158:159], v[158:159], v[94:95]
	v_add_co_u32_e32 v38, vcc, s9, v10
	s_nop 1
	v_addc_co_u32_e32 v39, vcc, -1, v11, vcc
	global_store_dwordx4 v[38:39], v[128:131], off offset:-3072
	global_store_dwordx4 v[38:39], v[132:135], off offset:-2048
	global_store_dwordx4 v[38:39], v[136:139], off offset:-1024
	global_store_dwordx4 v[10:11], v[140:143], off offset:-4096
	global_store_dwordx4 v[10:11], v[144:147], off offset:-3072
	global_store_dwordx4 v[10:11], v[148:151], off offset:-2048
	global_store_dwordx4 v[10:11], v[152:155], off offset:-1024
	global_store_dwordx4 v[10:11], v[156:159], off
